# v50 + gmlp_sample_item: the eight row-sum loads issued as one batch (second batch in v132-v147), no prefetch
# speedup vs baseline: 1.0007x; 1.0007x over previous
.LBB0_600:
	v_cmp_gt_i32_e32 vcc, 8, v119
	s_and_saveexec_b64 s[2:3], vcc
	s_cbranch_execz .LBB0_602
	v_readlane_b32 s0, v255, 34
	v_readlane_b32 s1, v255, 35
	v_lshl_add_u32 v0, v119, 2, 0
	v_add_u32_e32 v2, s0, v119
	v_ashrrev_i32_e32 v3, 31, v2
	v_lshlrev_b64 v[2:3], 7, v[2:3]
	v_lshl_add_u64 v[18:19], s[74:75], 0, v[2:3]
	global_load_dwordx4 v[2:5], v[18:19], off offset:48
	global_load_dwordx4 v[6:9], v[18:19], off offset:32
	global_load_dwordx4 v[10:13], v[18:19], off
	global_load_dwordx4 v[14:17], v[18:19], off offset:16
	global_load_dwordx4 v[132:135], v[18:19], off offset:112
	global_load_dwordx4 v[136:139], v[18:19], off offset:96
	global_load_dwordx4 v[140:143], v[18:19], off offset:80
	global_load_dwordx4 v[144:147], v[18:19], off offset:64
	s_waitcnt vmcnt(7)
	v_add_f32_e32 v24, v2, v3
	v_add_f32_e32 v26, v4, v5
	s_waitcnt vmcnt(5)
	v_mov_b32_e32 v20, v10
	s_waitcnt vmcnt(4)
	v_mov_b32_e32 v21, v14
	v_mov_b32_e32 v14, v11
	v_pk_add_f32 v[10:11], v[20:21], v[14:15]
	v_mov_b32_e32 v14, v12
	v_mov_b32_e32 v15, v16
	v_mov_b32_e32 v16, v13
	v_pk_add_f32 v[12:13], v[14:15], v[16:17]
	s_nop 0
	v_pk_add_f32 v[10:11], v[10:11], v[12:13]
	s_nop 0
	v_add_f32_e32 v10, 0, v10
	v_add_f32_e32 v20, v10, v11
	v_mov_b32_e32 v10, v7
	v_mov_b32_e32 v11, v8
	v_mov_b32_e32 v7, v9
	v_pk_add_f32 v[6:7], v[10:11], v[6:7]
	s_nop 0
	v_pk_add_f32 v[22:23], v[6:7], v[6:7] op_sel:[0,1] op_sel_hi:[1,0]
	s_waitcnt vmcnt(2)
	v_add_f32_e32 v136, v136, v137
	v_add_f32_e32 v138, v138, v139
	s_waitcnt vmcnt(0)
	v_mov_b32_e32 v21, v144
	v_mov_b32_e32 v23, v145
	v_mov_b32_e32 v25, v146
	v_mov_b32_e32 v27, v147
	v_pk_add_f32 v[144:145], v[20:21], v[22:23]
	v_pk_add_f32 v[146:147], v[24:25], v[26:27]
	v_mov_b32_e32 v137, v134
	v_pk_add_f32 v[144:145], v[144:145], v[146:147]
	v_mov_b32_e32 v146, v141
	v_mov_b32_e32 v147, v142
	v_mov_b32_e32 v141, v143
	v_pk_add_f32 v[140:141], v[146:147], v[140:141]
	v_pk_add_f32 v[144:145], v[144:145], v[144:145] op_sel:[0,1] op_sel_hi:[1,0]
	v_pk_add_f32 v[140:141], v[140:141], v[140:141] op_sel:[0,1] op_sel_hi:[1,0]
	v_mov_b32_e32 v145, v132
	v_mov_b32_e32 v141, v133
	v_mov_b32_e32 v139, v135
	v_pk_add_f32 v[132:133], v[144:145], v[140:141]
	v_pk_add_f32 v[134:135], v[136:137], v[138:139]
	s_nop 0
	v_pk_add_f32 v[132:133], v[132:133], v[134:135]
	s_nop 0
	v_add_f32_e32 v132, v132, v133
	v_fmamk_f32 v132, v132, 0x3a000000, v211
	v_cmp_gt_f32_e32 vcc, s94, v132
	v_mul_f32_e32 v133, 0x4f800000, v132
	s_nop 0
	v_cndmask_b32_e32 v132, v132, v133, vcc
	v_sqrt_f32_e32 v133, v132
	s_nop 0
	v_add_u32_e32 v134, -1, v133
	v_fma_f32 v135, -v134, v133, v132
	v_cmp_ge_f32_e64 s[0:1], 0, v135
	v_add_u32_e32 v135, 1, v133
	s_nop 0
	v_cndmask_b32_e64 v134, v133, v134, s[0:1]
	v_fma_f32 v133, -v135, v133, v132
	v_cmp_lt_f32_e64 s[0:1], 0, v133
	s_nop 1
	v_cndmask_b32_e64 v133, v134, v135, s[0:1]
	v_mul_f32_e32 v134, 0x37800000, v133
	v_cndmask_b32_e32 v133, v133, v134, vcc
	v_cmp_class_f32_e32 vcc, v132, v212
	s_nop 1
	v_cndmask_b32_e32 v132, v133, v132, vcc
	v_div_scale_f32 v133, s[0:1], v132, v132, 1.0
	v_rcp_f32_e32 v134, v133
	s_nop 0
	v_fma_f32 v135, -v133, v134, 1.0
	v_fmac_f32_e32 v134, v135, v134
	v_div_scale_f32 v135, vcc, 1.0, v132, 1.0
	v_mul_f32_e32 v136, v135, v134
	v_fma_f32 v137, -v133, v136, v135
	v_fmac_f32_e32 v136, v137, v134
	v_fma_f32 v133, -v133, v136, v135
	v_div_fmas_f32 v133, v133, v134, v136
	v_div_fixup_f32 v132, v133, v132, 1.0
	ds_write_b32 v0, v132
